# s5_c scan: d_skip quad loaded once per group in front of the block loop instead of a VMEM round trip per block
# baseline (speedup 1.0000x reference)
; #define LAS __attribute__((address_space(3)))
; __device__ __forceinline__ unsigned cvt_pk_bf16(float lo, float hi) { const bf16v2 v = __builtin_convertvector((f32x2){lo, hi}, bf16v2); return __builtin_bit_cast(unsigned, v); }
; __device__ __forceinline__ float bflo(unsigned w) { return __uint_as_float(w << 16); }
; __device__ __forceinline__ float bfhi(unsigned w) { return __uint_as_float(w & 0xffff0000u); }
; __device__ __forceinline__ u32x2 pack4(const f32x4 a) { u32x2 v; v.x = cvt_pk_bf16(a[0], a[1]); v.y = cvt_pk_bf16(a[2], a[3]); return v; }
; #define MFMA16(a, b, c) __builtin_amdgcn_mfma_f32_16x16x32_bf16((a), (b), (c), 0, 0, 0)
; __device__ __forceinline__ void s5_bu_block(const LAS bf16_t* UB, LAS bf16_t* XW, const bf16x8* bfrag, int blk, int g, int fr, int fq) {
;     bf16x8 af = (bf16x8){0, 0, 0, 0, 0, 0, 0, 0};
;     if (fq < 2) af = *(const LAS bf16x8*)(UB + (blk * 16 + fr) * 264 + g * 16 + fq * 8);
; #pragma unroll
;     for (int tile = 0; tile < 8; ++tile) { f32x4 acc = (f32x4){0.f, 0.f, 0.f, 0.f}; acc = MFMA16(bfrag[tile], af, acc);
;         *(LAS u32x2*)(XW + fr * 136 + tile * 16 + fq * 4) = pack4(acc); }
;     asm volatile("" ::: "memory");
; }
; __device__ void s5_c_unit(LAS unsigned char* lds, KP& P_, int l, int bc) {
;     ...
;     for (int gp = 0; gp < 2; ++gp) { const int g = gp * 8 + wid, n = lane;
;         bf16x8 bfrag[8]; s5_load_bfrag(P_, l, bfrag, g, fr, fq);
;         const f32x4 lam = *(const f32x4*)((const float*)(p.ws + TBL(T_S5LAM, l)) + (size_t)(g * 64 + n) * 4);
;         const f32x2 x0 = *(const f32x2*)((const float*)(p.ws + WS_STS) + (((size_t)bc * 16 + g) * 64 + n) * 2);
;         float xr = x0.x, xi = x0.y;
;         bf16x8 cf[4]; const bf16_t* cm = (const bf16_t*)(p.ws + TBL(T_S5C, l)) + (size_t)(g * 16 + fr) * 128;
; #pragma unroll
;         for (int ks = 0; ks < 4; ++ks) cf[ks] = *(const bf16x8*)(cm + ks * 32 + fq * 8);
;         const float* dsk = p.in[18] + l * 256 + g * 16 + fq * 4;
;         for (int blk = 0; blk < 4; ++blk) {
;             s5_bu_block(UB, XW, bfrag, blk, g, fr, fq);
; #pragma unroll
;             for (int tl = 0; tl < 16; ++tl) { LAS unsigned* wp = (LAS unsigned*)(XW + tl * 136 + 2 * n); const unsigned w = *wp;
;                 const float nr = lam[0] * xr - lam[1] * xi + bflo(w), ni = lam[0] * xi + lam[1] * xr + bfhi(w); xr = nr; xi = ni; *wp = cvt_pk_bf16(xr, xi); }
.LBB0_323:
	s_or_b64 exec, exec, s[14:15]
	v_bfe_u32 v56, v60, 4, 2
	v_lshlrev_b32_e32 v62, 3, v56
	s_add_u32 s46, s42, 0xef05000
	v_lshlrev_b32_e32 v0, 3, v88
	s_addc_u32 s47, s43, 0
	s_lshl_b32 s90, s22, 4
	v_lshl_add_u64 v[2:3], s[6:7], 0, v[0:1]
	s_mov_b64 s[14:15], 0xe790000
	v_lshlrev_b32_e32 v0, 1, v62
	v_ashrrev_i32_e32 v67, 31, v66
	v_lshl_add_u64 v[72:73], v[2:3], 0, s[14:15]
	v_lshl_add_u64 v[2:3], s[42:43], 0, v[0:1]
	v_ashrrev_i32_e32 v61, 31, v60
	v_lshl_add_u64 v[40:41], v[66:67], 0, s[90:91]
	v_lshl_add_u64 v[70:71], v[2:3], 0, s[38:39]
	v_lshl_add_u64 v[2:3], v[60:61], 4, s[46:47]
	v_lshlrev_b64 v[40:41], 9, v[40:41]
	v_lshlrev_b32_e32 v64, 4, v66
	v_lshl_add_u64 v[40:41], v[72:73], 0, v[40:41]
	global_load_dwordx2 v[76:77], v[2:3], off
	global_load_dwordx2 v[86:87], v[40:41], off
	v_or_b32_e32 v2, v64, v63
	v_ashrrev_i32_e32 v3, 31, v2
	v_lshlrev_b64 v[2:3], 8, v[2:3]
	v_lshl_add_u64 v[2:3], v[70:71], 0, v[2:3]
	global_load_dwordx4 v[40:43], v[2:3], off
	global_load_dwordx4 v[44:47], v[2:3], off offset:64
	global_load_dwordx4 v[48:51], v[2:3], off offset:128
	global_load_dwordx4 v[52:55], v[2:3], off offset:192
	s_lshl_b32 s14, s13, 8
	s_movk_i32 s12, 0x1100
	s_ashr_i32 s15, s14, 31
	v_mul_lo_u32 v0, v66, s12
	v_lshlrev_b32_e32 v58, 5, v66
	s_lshl_b64 s[44:45], s[14:15], 2
	v_and_b32_e32 v3, 48, v60
	v_add_u32_e32 v59, 0, v0
	v_mad_u32_u24 v0, v63, s26, v58
	s_waitcnt lgkmcnt(0)
	s_add_u32 s14, s48, s44
	s_movk_i32 s12, 0x110
	v_add_u32_e32 v94, v0, v3
	v_add3_u32 v61, v0, v62, 0
	v_lshlrev_b32_e32 v0, 4, v56
	s_addc_u32 s15, s49, s45
	v_lshlrev_b32_e32 v57, 2, v88
	v_ashrrev_i32_e32 v65, 31, v64
	v_mad_u32_u24 v67, v63, s12, v59
	v_lshl_add_u64 v[74:75], s[14:15], 0, v[0:1]
	v_lshlrev_b32_e32 v2, 2, v56
	v_add_u32_e32 v95, 0, v94
	v_lshl_add_u64 v[78:79], v[64:65], 2, v[74:75]
	v_add_u32_e32 v96, v67, v62
	v_add_u32_e32 v97, v59, v57
	s_waitcnt vmcnt(5)
	v_mov_b32_e32 v80, v76
	v_mov_b32_e32 v81, v76
	v_mov_b32_e32 v82, v77
	v_mov_b32_e32 v83, v77
	v_pk_mov_b32 v[84:85], v[76:77], v[76:77] op_sel:[1,0]
	s_waitcnt vmcnt(4)
	v_mov_b32_e32 v0, v87
	global_load_dwordx4 v[242:245], v[78:79], off
	s_branch .LBB0_325
.LBB0_324:
	s_or_b64 exec, exec, s[14:15]
	s_waitcnt lgkmcnt(0)
	v_mfma_f32_16x16x32_bf16 v[90:93], v[16:19], v[56:59], 0
	v_add_u32_e32 v65, 0x8000, v96
	v_add_u32_e32 v89, 0x8400, v97
	s_nop 5
	v_cvt_pk_bf16_f32 v98, v90, v91
	v_cvt_pk_bf16_f32 v99, v92, v93
	v_mfma_f32_16x16x32_bf16 v[90:93], v[12:15], v[56:59], 0
	s_nop 7
	v_cvt_pk_bf16_f32 v90, v90, v91
	v_cvt_pk_bf16_f32 v91, v92, v93
	ds_write2_b64 v65, v[98:99], v[90:91] offset0:128 offset1:132
	v_mfma_f32_16x16x32_bf16 v[90:93], v[20:23], v[56:59], 0
	s_nop 7
	v_cvt_pk_bf16_f32 v98, v90, v91
	v_cvt_pk_bf16_f32 v99, v92, v93
	v_mfma_f32_16x16x32_bf16 v[90:93], v[8:11], v[56:59], 0
	s_nop 7
	v_cvt_pk_bf16_f32 v90, v90, v91
	v_cvt_pk_bf16_f32 v91, v92, v93
	ds_write2_b64 v65, v[98:99], v[90:91] offset0:136 offset1:140
	v_mfma_f32_16x16x32_bf16 v[90:93], v[32:35], v[56:59], 0
	s_nop 7
	v_cvt_pk_bf16_f32 v98, v90, v91
	v_cvt_pk_bf16_f32 v99, v92, v93
	v_mfma_f32_16x16x32_bf16 v[90:93], v[28:31], v[56:59], 0
	s_nop 7
	v_cvt_pk_bf16_f32 v90, v90, v91
	v_cvt_pk_bf16_f32 v91, v92, v93
	ds_write2_b64 v65, v[98:99], v[90:91] offset0:144 offset1:148
	v_mfma_f32_16x16x32_bf16 v[90:93], v[36:39], v[56:59], 0
	v_mfma_f32_16x16x32_bf16 v[56:59], v[24:27], v[56:59], 0
	s_nop 6
	v_cvt_pk_bf16_f32 v90, v90, v91
	v_cvt_pk_bf16_f32 v91, v92, v93
	v_cvt_pk_bf16_f32 v56, v56, v57
	v_cvt_pk_bf16_f32 v57, v58, v59
	ds_write2_b64 v65, v[90:91], v[56:57] offset0:152 offset1:156
	ds_read2_b32 v[56:57], v89 offset1:68
	v_pk_mul_f32 v[58:59], v[84:85], v[0:1] op_sel_hi:[1,0]
	s_waitcnt lgkmcnt(0)
	v_lshlrev_b32_e32 v90, 16, v56
	v_pk_fma_f32 v[92:93], v[76:77], v[86:87], v[58:59] neg_lo:[0,0,1] neg_hi:[0,0,1]
	v_pk_fma_f32 v[58:59], v[76:77], v[86:87], v[58:59] op_sel_hi:[1,0,1]
	v_and_b32_e32 v91, 0xffff0000, v56
	v_mov_b32_e32 v93, v59
	v_pk_add_f32 v[58:59], v[92:93], v[90:91]
	v_lshlrev_b32_e32 v56, 16, v57
	v_pk_mul_f32 v[86:87], v[82:83], v[58:59]
	v_cvt_pk_bf16_f32 v0, v58, v59
	v_pk_fma_f32 v[90:91], v[80:81], v[58:59], v[86:87] op_sel:[0,0,1] op_sel_hi:[1,1,0] neg_lo:[0,0,1] neg_hi:[0,0,1]
	v_pk_fma_f32 v[58:59], v[80:81], v[58:59], v[86:87] op_sel:[0,0,1] op_sel_hi:[1,1,0]
	v_and_b32_e32 v57, 0xffff0000, v57
	v_mov_b32_e32 v91, v59
	v_pk_add_f32 v[56:57], v[90:91], v[56:57]
	s_nop 0
	v_cvt_pk_bf16_f32 v58, v56, v57
	ds_write2_b32 v89, v0, v58 offset1:68
	ds_read2_b32 v[58:59], v89 offset0:136 offset1:204
	v_pk_mul_f32 v[90:91], v[82:83], v[56:57]
	s_waitcnt lgkmcnt(0)
	v_lshlrev_b32_e32 v86, 16, v58
	v_pk_fma_f32 v[92:93], v[80:81], v[56:57], v[90:91] op_sel:[0,0,1] op_sel_hi:[1,1,0] neg_lo:[0,0,1] neg_hi:[0,0,1]
	v_pk_fma_f32 v[56:57], v[80:81], v[56:57], v[90:91] op_sel:[0,0,1] op_sel_hi:[1,1,0]
	v_and_b32_e32 v87, 0xffff0000, v58
	v_mov_b32_e32 v93, v57
	v_pk_add_f32 v[56:57], v[92:93], v[86:87]
	v_lshlrev_b32_e32 v58, 16, v59
	v_pk_mul_f32 v[86:87], v[82:83], v[56:57]
	v_cvt_pk_bf16_f32 v0, v56, v57
	v_pk_fma_f32 v[90:91], v[80:81], v[56:57], v[86:87] op_sel:[0,0,1] op_sel_hi:[1,1,0] neg_lo:[0,0,1] neg_hi:[0,0,1]
	v_pk_fma_f32 v[56:57], v[80:81], v[56:57], v[86:87] op_sel:[0,0,1] op_sel_hi:[1,1,0]
	v_and_b32_e32 v59, 0xffff0000, v59
	v_mov_b32_e32 v91, v57
	v_pk_add_f32 v[56:57], v[90:91], v[58:59]
	v_add_u32_e32 v90, 0x8800, v97
	v_cvt_pk_bf16_f32 v58, v56, v57
	ds_write2_b32 v89, v0, v58 offset0:136 offset1:204
	ds_read2_b32 v[58:59], v90 offset0:16 offset1:84
	v_pk_mul_f32 v[92:93], v[82:83], v[56:57]
	v_add_u32_e32 v91, 0x8c00, v97
	v_pk_fma_f32 v[98:99], v[80:81], v[56:57], v[92:93] op_sel:[0,0,1] op_sel_hi:[1,1,0] neg_lo:[0,0,1] neg_hi:[0,0,1]
	v_pk_fma_f32 v[56:57], v[80:81], v[56:57], v[92:93] op_sel:[0,0,1] op_sel_hi:[1,1,0]
	s_waitcnt lgkmcnt(0)
; #define LAS __attribute__((address_space(3)))
; __device__ __forceinline__ unsigned cvt_pk_bf16(float lo, float hi) { const bf16v2 v = __builtin_convertvector((f32x2){lo, hi}, bf16v2); return __builtin_bit_cast(unsigned, v); }
; __device__ __forceinline__ float bflo(unsigned w) { return __uint_as_float(w << 16); }
; __device__ __forceinline__ float bfhi(unsigned w) { return __uint_as_float(w & 0xffff0000u); }
; __device__ void s5_c_unit(LAS unsigned char* lds, KP& P_, int l, int bc) {
;     ...
; #pragma unroll
;             for (int tl = 0; tl < 16; ++tl) { LAS unsigned* wp = (LAS unsigned*)(XW + tl * 136 + 2 * n); const unsigned w = *wp;
;                 const float nr = lam[0] * xr - lam[1] * xi + bflo(w), ni = lam[0] * xi + lam[1] * xr + bfhi(w); xr = nr; xi = ni; *wp = cvt_pk_bf16(xr, xi); }
	v_lshlrev_b32_e32 v86, 16, v58
	v_and_b32_e32 v87, 0xffff0000, v58
	v_mov_b32_e32 v99, v57
	v_pk_add_f32 v[56:57], v[98:99], v[86:87]
	v_lshlrev_b32_e32 v58, 16, v59
	v_pk_mul_f32 v[86:87], v[82:83], v[56:57]
	v_cvt_pk_bf16_f32 v0, v56, v57
	v_pk_fma_f32 v[92:93], v[80:81], v[56:57], v[86:87] op_sel:[0,0,1] op_sel_hi:[1,1,0] neg_lo:[0,0,1] neg_hi:[0,0,1]
	v_pk_fma_f32 v[56:57], v[80:81], v[56:57], v[86:87] op_sel:[0,0,1] op_sel_hi:[1,1,0]
	v_and_b32_e32 v59, 0xffff0000, v59
	v_mov_b32_e32 v93, v57
	v_pk_add_f32 v[56:57], v[92:93], v[58:59]
	s_nop 0
	v_cvt_pk_bf16_f32 v58, v56, v57
	ds_write2_b32 v90, v0, v58 offset0:16 offset1:84
	ds_read2_b32 v[58:59], v90 offset0:152 offset1:220
	v_pk_mul_f32 v[92:93], v[82:83], v[56:57]
	s_waitcnt lgkmcnt(0)
	v_lshlrev_b32_e32 v86, 16, v58
	v_pk_fma_f32 v[98:99], v[80:81], v[56:57], v[92:93] op_sel:[0,0,1] op_sel_hi:[1,1,0] neg_lo:[0,0,1] neg_hi:[0,0,1]
	v_pk_fma_f32 v[56:57], v[80:81], v[56:57], v[92:93] op_sel:[0,0,1] op_sel_hi:[1,1,0]
	v_and_b32_e32 v87, 0xffff0000, v58
	v_mov_b32_e32 v99, v57
	v_pk_add_f32 v[56:57], v[98:99], v[86:87]
	v_lshlrev_b32_e32 v58, 16, v59
	v_pk_mul_f32 v[86:87], v[82:83], v[56:57]
	v_cvt_pk_bf16_f32 v0, v56, v57
	v_pk_fma_f32 v[92:93], v[80:81], v[56:57], v[86:87] op_sel:[0,0,1] op_sel_hi:[1,1,0] neg_lo:[0,0,1] neg_hi:[0,0,1]
	v_pk_fma_f32 v[56:57], v[80:81], v[56:57], v[86:87] op_sel:[0,0,1] op_sel_hi:[1,1,0]
	v_and_b32_e32 v59, 0xffff0000, v59
	v_mov_b32_e32 v93, v57
	v_pk_add_f32 v[56:57], v[92:93], v[58:59]
	s_nop 0
	v_cvt_pk_bf16_f32 v58, v56, v57
	ds_write2_b32 v90, v0, v58 offset0:152 offset1:220
	ds_read2_b32 v[58:59], v91 offset0:32 offset1:100
	v_pk_mul_f32 v[92:93], v[82:83], v[56:57]
	s_waitcnt lgkmcnt(0)
	v_lshlrev_b32_e32 v86, 16, v58
	v_pk_fma_f32 v[98:99], v[80:81], v[56:57], v[92:93] op_sel:[0,0,1] op_sel_hi:[1,1,0] neg_lo:[0,0,1] neg_hi:[0,0,1]
	v_pk_fma_f32 v[56:57], v[80:81], v[56:57], v[92:93] op_sel:[0,0,1] op_sel_hi:[1,1,0]
	v_and_b32_e32 v87, 0xffff0000, v58
	v_mov_b32_e32 v99, v57
	v_pk_add_f32 v[56:57], v[98:99], v[86:87]
	v_lshlrev_b32_e32 v58, 16, v59
	v_pk_mul_f32 v[86:87], v[82:83], v[56:57]
	v_cvt_pk_bf16_f32 v0, v56, v57
	v_pk_fma_f32 v[92:93], v[80:81], v[56:57], v[86:87] op_sel:[0,0,1] op_sel_hi:[1,1,0] neg_lo:[0,0,1] neg_hi:[0,0,1]
	v_pk_fma_f32 v[56:57], v[80:81], v[56:57], v[86:87] op_sel:[0,0,1] op_sel_hi:[1,1,0]
	v_and_b32_e32 v59, 0xffff0000, v59
	v_mov_b32_e32 v93, v57
	v_pk_add_f32 v[56:57], v[92:93], v[58:59]
	s_nop 0
	v_cvt_pk_bf16_f32 v58, v56, v57
	ds_write2_b32 v91, v0, v58 offset0:32 offset1:100
	ds_read2_b32 v[58:59], v91 offset0:168 offset1:236
	v_pk_mul_f32 v[92:93], v[82:83], v[56:57]
	s_waitcnt lgkmcnt(0)
	v_lshlrev_b32_e32 v86, 16, v58
	v_pk_fma_f32 v[98:99], v[80:81], v[56:57], v[92:93] op_sel:[0,0,1] op_sel_hi:[1,1,0] neg_lo:[0,0,1] neg_hi:[0,0,1]
	v_pk_fma_f32 v[56:57], v[80:81], v[56:57], v[92:93] op_sel:[0,0,1] op_sel_hi:[1,1,0]
	v_and_b32_e32 v87, 0xffff0000, v58
	v_mov_b32_e32 v99, v57
	v_pk_add_f32 v[56:57], v[98:99], v[86:87]
	v_lshlrev_b32_e32 v58, 16, v59
	v_pk_mul_f32 v[86:87], v[82:83], v[56:57]
	v_cvt_pk_bf16_f32 v0, v56, v57
	v_pk_fma_f32 v[92:93], v[80:81], v[56:57], v[86:87] op_sel:[0,0,1] op_sel_hi:[1,1,0] neg_lo:[0,0,1] neg_hi:[0,0,1]
	v_pk_fma_f32 v[56:57], v[80:81], v[56:57], v[86:87] op_sel:[0,0,1] op_sel_hi:[1,1,0]
	v_and_b32_e32 v59, 0xffff0000, v59
	v_mov_b32_e32 v93, v57
	v_pk_add_f32 v[56:57], v[92:93], v[58:59]
	v_add_u32_e32 v92, 0x9000, v97
	v_cvt_pk_bf16_f32 v58, v56, v57
	ds_write2_b32 v91, v0, v58 offset0:168 offset1:236
	ds_read2_b32 v[58:59], v92 offset0:48 offset1:116
	v_pk_mul_f32 v[98:99], v[82:83], v[56:57]
	v_add_u32_e32 v93, v67, v3
	v_pk_fma_f32 v[100:101], v[80:81], v[56:57], v[98:99] op_sel:[0,0,1] op_sel_hi:[1,1,0] neg_lo:[0,0,1] neg_hi:[0,0,1]
	v_pk_fma_f32 v[56:57], v[80:81], v[56:57], v[98:99] op_sel:[0,0,1] op_sel_hi:[1,1,0]
	s_waitcnt lgkmcnt(0)
; #define LAS __attribute__((address_space(3)))
; __device__ __forceinline__ unsigned cvt_pk_bf16(float lo, float hi) { const bf16v2 v = __builtin_convertvector((f32x2){lo, hi}, bf16v2); return __builtin_bit_cast(unsigned, v); }
; __device__ __forceinline__ float bflo(unsigned w) { return __uint_as_float(w << 16); }
; __device__ __forceinline__ float bfhi(unsigned w) { return __uint_as_float(w & 0xffff0000u); }
; __device__ __forceinline__ u32x2 pack4(const f32x4 a) { u32x2 v; v.x = cvt_pk_bf16(a[0], a[1]); v.y = cvt_pk_bf16(a[2], a[3]); return v; }
; __device__ __forceinline__ float gelu_tanh(float x) { const float e = __builtin_amdgcn_exp2f(x * (-2.302208198f - 0.102943240f * x * x)); return x * __builtin_amdgcn_rcpf(1.0f + e); }
; #define MFMA16(a, b, c) __builtin_amdgcn_mfma_f32_16x16x32_bf16((a), (b), (c), 0, 0, 0)
; __device__ void s5_c_unit(LAS unsigned char* lds, KP& P_, int l, int bc) {
;     ...
; #pragma unroll
;             for (int tl = 0; tl < 16; ++tl) { LAS unsigned* wp = (LAS unsigned*)(XW + tl * 136 + 2 * n); const unsigned w = *wp;
;                 const float nr = lam[0] * xr - lam[1] * xi + bflo(w), ni = lam[0] * xi + lam[1] * xr + bfhi(w); xr = nr; xi = ni; *wp = cvt_pk_bf16(xr, xi); }
;             asm volatile("" ::: "memory");
;             f32x4 acc = (f32x4){0.f, 0.f, 0.f, 0.f};
; #pragma unroll
;             for (int ks = 0; ks < 4; ++ks) { const bf16x8 b = *(const LAS bf16x8*)(XW + fr * 136 + ks * 32 + fq * 8); acc = MFMA16(cf[ks], b, acc); }
;             const int t = blk * 16 + fr; const u32x2 uraw = *(const LAS u32x2*)(UB + t * 264 + g * 16 + fq * 4);
;             const float uv[4] = {bflo(uraw.x), bfhi(uraw.x), bflo(uraw.y), bfhi(uraw.y)}; f32x4 y;
; #pragma unroll
;             for (int j = 0; j < 4; ++j) y[j] = gelu_tanh(acc[j] + dsk[j] * uv[j]);
;             *(LAS u32x2*)(YG + t * 264 + g * 16 + fq * 4) = pack4(y);
;             asm volatile("" ::: "memory");
	v_lshlrev_b32_e32 v86, 16, v58
	v_and_b32_e32 v87, 0xffff0000, v58
	v_mov_b32_e32 v101, v57
	v_pk_add_f32 v[56:57], v[100:101], v[86:87]
	v_lshlrev_b32_e32 v58, 16, v59
	v_pk_mul_f32 v[86:87], v[82:83], v[56:57]
	v_cvt_pk_bf16_f32 v0, v56, v57
	v_pk_fma_f32 v[98:99], v[80:81], v[56:57], v[86:87] op_sel:[0,0,1] op_sel_hi:[1,1,0] neg_lo:[0,0,1] neg_hi:[0,0,1]
	v_pk_fma_f32 v[56:57], v[80:81], v[56:57], v[86:87] op_sel:[0,0,1] op_sel_hi:[1,1,0]
	v_and_b32_e32 v59, 0xffff0000, v59
	v_mov_b32_e32 v99, v57
	v_pk_add_f32 v[56:57], v[98:99], v[58:59]
	s_nop 0
	v_cvt_pk_bf16_f32 v58, v56, v57
	ds_write2_b32 v92, v0, v58 offset0:48 offset1:116
	ds_read2_b32 v[58:59], v92 offset0:184 offset1:252
	v_pk_mul_f32 v[98:99], v[82:83], v[56:57]
	s_waitcnt lgkmcnt(0)
	v_lshlrev_b32_e32 v86, 16, v58
	v_pk_fma_f32 v[100:101], v[80:81], v[56:57], v[98:99] op_sel:[0,0,1] op_sel_hi:[1,1,0] neg_lo:[0,0,1] neg_hi:[0,0,1]
	v_pk_fma_f32 v[56:57], v[80:81], v[56:57], v[98:99] op_sel:[0,0,1] op_sel_hi:[1,1,0]
	v_and_b32_e32 v87, 0xffff0000, v58
	v_mov_b32_e32 v101, v57
	v_pk_add_f32 v[56:57], v[100:101], v[86:87]
	v_lshlrev_b32_e32 v58, 16, v59
	v_pk_mul_f32 v[86:87], v[82:83], v[56:57]
	v_cvt_pk_bf16_f32 v0, v56, v57
	v_pk_fma_f32 v[98:99], v[80:81], v[56:57], v[86:87] op_sel:[0,0,1] op_sel_hi:[1,1,0] neg_lo:[0,0,1] neg_hi:[0,0,1]
	v_pk_fma_f32 v[56:57], v[80:81], v[56:57], v[86:87] op_sel:[0,0,1] op_sel_hi:[1,1,0]
	v_and_b32_e32 v59, 0xffff0000, v59
	v_mov_b32_e32 v99, v57
	v_pk_add_f32 v[86:87], v[98:99], v[58:59]
	s_nop 0
	v_cvt_pk_bf16_f32 v56, v86, v87
	ds_write2_b32 v92, v0, v56 offset0:184 offset1:252
	ds_read_b128 v[56:59], v93 offset:33792
	ds_read_b128 v[98:101], v93 offset:33856
	v_add_u32_e32 v0, s23, v61
	ds_read_b64 v[102:103], v0
	s_waitcnt vmcnt(3) lgkmcnt(2)
	v_mfma_f32_16x16x32_bf16 v[56:59], v[40:43], v[56:59], 0
	v_add_u32_e32 v0, 0x10c00, v0
	s_addk_i32 s23, 0x2100
	s_waitcnt lgkmcnt(0)
	v_lshlrev_b32_e32 v104, 16, v102
	s_waitcnt vmcnt(2)
	v_mfma_f32_16x16x32_bf16 v[56:59], v[44:47], v[98:101], v[56:59]
	ds_read_b128 v[98:101], v93 offset:33920
	v_and_b32_e32 v105, 0xffff0000, v102
	s_cmpk_eq_u32 s23, 0x8400
	s_waitcnt vmcnt(1) lgkmcnt(0)
	v_mfma_f32_16x16x32_bf16 v[56:59], v[48:51], v[98:101], v[56:59]
	ds_read_b128 v[98:101], v93 offset:33984
	s_waitcnt vmcnt(0) lgkmcnt(0)
	v_mfma_f32_16x16x32_bf16 v[56:59], v[52:55], v[98:101], v[56:59]
	s_nop 7
	v_pk_fma_f32 v[56:57], v[242:243], v[104:105], v[56:57]
	s_nop 0
	v_mul_f32_e32 v98, 0x3dd2d3e8, v56
	v_mul_f32_e32 v99, 0x3dd2d3e8, v57
	v_fma_f32 v98, -v56, v98, s92
	v_fma_f32 v99, -v57, v99, s92
	v_mul_f32_e32 v98, v56, v98
	v_mul_f32_e32 v99, v57, v99
	v_exp_f32_e32 v98, v98
	v_exp_f32_e32 v99, v99
	v_add_f32_e32 v98, 1.0, v98
	v_add_f32_e32 v99, 1.0, v99
	v_rcp_f32_e32 v98, v98
	v_rcp_f32_e32 v99, v99
	s_nop 0
	v_pk_mul_f32 v[56:57], v[56:57], v[98:99]
	v_lshlrev_b32_e32 v98, 16, v103
	v_and_b32_e32 v99, 0xffff0000, v103
	v_pk_fma_f32 v[58:59], v[244:245], v[98:99], v[58:59]
	v_cvt_pk_bf16_f32 v56, v56, v57
	v_mul_f32_e32 v98, 0x3dd2d3e8, v58
	v_mul_f32_e32 v99, 0x3dd2d3e8, v59
	v_fma_f32 v98, -v58, v98, s92
	v_fma_f32 v99, -v59, v99, s92
	v_mul_f32_e32 v98, v58, v98
	v_mul_f32_e32 v99, v59, v99
	v_exp_f32_e32 v98, v98
	v_exp_f32_e32 v99, v99
	v_add_f32_e32 v98, 1.0, v98
	v_add_f32_e32 v99, 1.0, v99
	v_rcp_f32_e32 v98, v98
	v_rcp_f32_e32 v99, v99
	s_nop 0
	v_pk_mul_f32 v[58:59], v[58:59], v[98:99]
	s_nop 0
	v_cvt_pk_bf16_f32 v57, v58, v59
	ds_write_b64 v0, v[56:57]
	v_mov_b32_e32 v0, v87
	s_cbranch_scc1 .LBB0_327

; #define LAS __attribute__((address_space(3)))
; __device__ __forceinline__ unsigned cvt_pk_bf16(float lo, float hi) { const bf16v2 v = __builtin_convertvector((f32x2){lo, hi}, bf16v2); return __builtin_bit_cast(unsigned, v); }
; __device__ __forceinline__ float bflo(unsigned w) { return __uint_as_float(w << 16); }
; __device__ __forceinline__ float bfhi(unsigned w) { return __uint_as_float(w & 0xffff0000u); }
; __device__ __forceinline__ u32x2 pack4(const f32x4 a) { u32x2 v; v.x = cvt_pk_bf16(a[0], a[1]); v.y = cvt_pk_bf16(a[2], a[3]); return v; }
; #define MFMA16(a, b, c) __builtin_amdgcn_mfma_f32_16x16x32_bf16((a), (b), (c), 0, 0, 0)
; __device__ __forceinline__ void s5_bu_block(const LAS bf16_t* UB, LAS bf16_t* XW, const bf16x8* bfrag, int blk, int g, int fr, int fq) {
;     bf16x8 af = (bf16x8){0, 0, 0, 0, 0, 0, 0, 0};
;     if (fq < 2) af = *(const LAS bf16x8*)(UB + (blk * 16 + fr) * 264 + g * 16 + fq * 8);
; #pragma unroll
;     for (int tile = 0; tile < 8; ++tile) { f32x4 acc = (f32x4){0.f, 0.f, 0.f, 0.f}; acc = MFMA16(bfrag[tile], af, acc);
;         *(LAS u32x2*)(XW + fr * 136 + tile * 16 + fq * 4) = pack4(acc); }
;     asm volatile("" ::: "memory");
; }
; __device__ void s5_c_unit(LAS unsigned char* lds, KP& P_, int l, int bc) {
;     ...
;     for (int gp = 0; gp < 2; ++gp) { const int g = gp * 8 + wid, n = lane;
;         bf16x8 bfrag[8]; s5_load_bfrag(P_, l, bfrag, g, fr, fq);
;         const f32x4 lam = *(const f32x4*)((const float*)(p.ws + TBL(T_S5LAM, l)) + (size_t)(g * 64 + n) * 4);
;         const f32x2 x0 = *(const f32x2*)((const float*)(p.ws + WS_STS) + (((size_t)bc * 16 + g) * 64 + n) * 2);
;         float xr = x0.x, xi = x0.y;
;         bf16x8 cf[4]; const bf16_t* cm = (const bf16_t*)(p.ws + TBL(T_S5C, l)) + (size_t)(g * 16 + fr) * 128;
; #pragma unroll
;         for (int ks = 0; ks < 4; ++ks) cf[ks] = *(const bf16x8*)(cm + ks * 32 + fq * 8);
;         const float* dsk = p.in[18] + l * 256 + g * 16 + fq * 4;
;         for (int blk = 0; blk < 4; ++blk) {
;             s5_bu_block(UB, XW, bfrag, blk, g, fr, fq);
; #pragma unroll
;             for (int tl = 0; tl < 16; ++tl) { LAS unsigned* wp = (LAS unsigned*)(XW + tl * 136 + 2 * n); const unsigned w = *wp;
;                 const float nr = lam[0] * xr - lam[1] * xi + bflo(w), ni = lam[0] * xi + lam[1] * xr + bfhi(w); xr = nr; xi = ni; *wp = cvt_pk_bf16(xr, xi); }
.LBB0_335:
	s_or_b64 exec, exec, s[14:15]
	v_ashrrev_i32_e32 v41, 31, v40
	v_lshlrev_b32_e32 v56, 4, v40
	v_lshl_or_b32 v42, v40, 6, v88
	v_lshl_add_u64 v[44:45], v[40:41], 0, s[90:91]
	v_or_b32_e32 v40, v56, v63
	v_ashrrev_i32_e32 v41, 31, v40
	v_ashrrev_i32_e32 v43, 31, v42
	v_lshlrev_b64 v[44:45], 9, v[44:45]
	v_lshlrev_b64 v[40:41], 8, v[40:41]
	v_lshl_add_u64 v[42:43], v[42:43], 4, s[46:47]
	v_lshl_add_u64 v[44:45], v[72:73], 0, v[44:45]
	v_lshl_add_u64 v[52:53], v[70:71], 0, v[40:41]
	global_load_dwordx2 v[66:67], v[42:43], off
	global_load_dwordx2 v[76:77], v[44:45], off
	s_nop 0
	global_load_dwordx4 v[40:43], v[52:53], off
	global_load_dwordx4 v[44:47], v[52:53], off offset:64
	global_load_dwordx4 v[48:51], v[52:53], off offset:128
	s_nop 0
	global_load_dwordx4 v[52:55], v[52:53], off offset:192
	s_add_i32 s12, 0, 0x100
	v_ashrrev_i32_e32 v57, 31, v56
	v_lshl_add_u64 v[68:69], v[56:57], 2, v[74:75]
	v_add_u32_e32 v78, s12, v94
	s_waitcnt vmcnt(5)
	v_mov_b32_e32 v70, v66
	v_mov_b32_e32 v71, v66
	v_mov_b32_e32 v72, v67
	v_mov_b32_e32 v73, v67
	v_pk_mov_b32 v[74:75], v[66:67], v[66:67] op_sel:[1,0]
	s_waitcnt vmcnt(4)
	v_mov_b32_e32 v0, v77
	global_load_dwordx4 v[246:249], v[68:69], off
	s_branch .LBB0_337
.LBB0_336:
	s_or_b64 exec, exec, s[14:15]
	s_waitcnt lgkmcnt(0)
	v_mfma_f32_16x16x32_bf16 v[80:83], v[16:19], v[56:59], 0
	s_nop 7
	v_cvt_pk_bf16_f32 v84, v80, v81
	v_cvt_pk_bf16_f32 v85, v82, v83
	v_mfma_f32_16x16x32_bf16 v[80:83], v[12:15], v[56:59], 0
	s_nop 7
	v_cvt_pk_bf16_f32 v80, v80, v81
	v_cvt_pk_bf16_f32 v81, v82, v83
	ds_write2_b64 v65, v[84:85], v[80:81] offset0:128 offset1:132
	v_mfma_f32_16x16x32_bf16 v[80:83], v[20:23], v[56:59], 0
	s_nop 7
	v_cvt_pk_bf16_f32 v84, v80, v81
	v_cvt_pk_bf16_f32 v85, v82, v83
	v_mfma_f32_16x16x32_bf16 v[80:83], v[8:11], v[56:59], 0
	s_nop 7
	v_cvt_pk_bf16_f32 v80, v80, v81
	v_cvt_pk_bf16_f32 v81, v82, v83
	ds_write2_b64 v65, v[84:85], v[80:81] offset0:136 offset1:140
	v_mfma_f32_16x16x32_bf16 v[80:83], v[32:35], v[56:59], 0
	s_nop 7
	v_cvt_pk_bf16_f32 v84, v80, v81
	v_cvt_pk_bf16_f32 v85, v82, v83
	v_mfma_f32_16x16x32_bf16 v[80:83], v[28:31], v[56:59], 0
	s_nop 7
	v_cvt_pk_bf16_f32 v80, v80, v81
	v_cvt_pk_bf16_f32 v81, v82, v83
	ds_write2_b64 v65, v[84:85], v[80:81] offset0:144 offset1:148
	v_mfma_f32_16x16x32_bf16 v[80:83], v[36:39], v[56:59], 0
	v_mfma_f32_16x16x32_bf16 v[56:59], v[24:27], v[56:59], 0
	s_nop 6
	v_cvt_pk_bf16_f32 v80, v80, v81
	v_cvt_pk_bf16_f32 v81, v82, v83
	v_cvt_pk_bf16_f32 v56, v56, v57
	v_cvt_pk_bf16_f32 v57, v58, v59
	ds_write2_b64 v65, v[80:81], v[56:57] offset0:152 offset1:156
	ds_read2_b32 v[56:57], v89 offset1:68
	v_pk_mul_f32 v[58:59], v[74:75], v[0:1] op_sel_hi:[1,0]
	s_waitcnt lgkmcnt(0)
	v_lshlrev_b32_e32 v80, 16, v56
	v_pk_fma_f32 v[82:83], v[66:67], v[76:77], v[58:59] neg_lo:[0,0,1] neg_hi:[0,0,1]
	v_pk_fma_f32 v[58:59], v[66:67], v[76:77], v[58:59] op_sel_hi:[1,0,1]
	v_and_b32_e32 v81, 0xffff0000, v56
	v_mov_b32_e32 v83, v59
	v_pk_add_f32 v[58:59], v[82:83], v[80:81]
	v_lshlrev_b32_e32 v56, 16, v57
	v_pk_mul_f32 v[76:77], v[72:73], v[58:59]
	v_cvt_pk_bf16_f32 v0, v58, v59
	v_pk_fma_f32 v[80:81], v[70:71], v[58:59], v[76:77] op_sel:[0,0,1] op_sel_hi:[1,1,0] neg_lo:[0,0,1] neg_hi:[0,0,1]
	v_pk_fma_f32 v[58:59], v[70:71], v[58:59], v[76:77] op_sel:[0,0,1] op_sel_hi:[1,1,0]
	v_and_b32_e32 v57, 0xffff0000, v57
	v_mov_b32_e32 v81, v59
	v_pk_add_f32 v[56:57], v[80:81], v[56:57]
	s_nop 0
	v_cvt_pk_bf16_f32 v58, v56, v57
	ds_write2_b32 v89, v0, v58 offset1:68
	ds_read2_b32 v[58:59], v89 offset0:136 offset1:204
	v_pk_mul_f32 v[80:81], v[72:73], v[56:57]
	s_waitcnt lgkmcnt(0)
	v_lshlrev_b32_e32 v76, 16, v58
	v_pk_fma_f32 v[82:83], v[70:71], v[56:57], v[80:81] op_sel:[0,0,1] op_sel_hi:[1,1,0] neg_lo:[0,0,1] neg_hi:[0,0,1]
	v_pk_fma_f32 v[56:57], v[70:71], v[56:57], v[80:81] op_sel:[0,0,1] op_sel_hi:[1,1,0]
	v_and_b32_e32 v77, 0xffff0000, v58
	v_mov_b32_e32 v83, v57
	v_pk_add_f32 v[56:57], v[82:83], v[76:77]
	v_lshlrev_b32_e32 v58, 16, v59
	v_pk_mul_f32 v[76:77], v[72:73], v[56:57]
	v_cvt_pk_bf16_f32 v0, v56, v57
	v_pk_fma_f32 v[80:81], v[70:71], v[56:57], v[76:77] op_sel:[0,0,1] op_sel_hi:[1,1,0] neg_lo:[0,0,1] neg_hi:[0,0,1]
	v_pk_fma_f32 v[56:57], v[70:71], v[56:57], v[76:77] op_sel:[0,0,1] op_sel_hi:[1,1,0]
	v_and_b32_e32 v59, 0xffff0000, v59
	v_mov_b32_e32 v81, v57
	v_pk_add_f32 v[56:57], v[80:81], v[58:59]
	s_nop 0
	v_cvt_pk_bf16_f32 v58, v56, v57
	ds_write2_b32 v89, v0, v58 offset0:136 offset1:204
	ds_read2_b32 v[58:59], v90 offset0:16 offset1:84
	v_pk_mul_f32 v[80:81], v[72:73], v[56:57]
	s_waitcnt lgkmcnt(0)
	v_lshlrev_b32_e32 v76, 16, v58
	v_pk_fma_f32 v[82:83], v[70:71], v[56:57], v[80:81] op_sel:[0,0,1] op_sel_hi:[1,1,0] neg_lo:[0,0,1] neg_hi:[0,0,1]
	v_pk_fma_f32 v[56:57], v[70:71], v[56:57], v[80:81] op_sel:[0,0,1] op_sel_hi:[1,1,0]
	v_and_b32_e32 v77, 0xffff0000, v58
	v_mov_b32_e32 v83, v57
	v_pk_add_f32 v[56:57], v[82:83], v[76:77]
	v_lshlrev_b32_e32 v58, 16, v59
	v_pk_mul_f32 v[76:77], v[72:73], v[56:57]
	v_cvt_pk_bf16_f32 v0, v56, v57
	v_pk_fma_f32 v[80:81], v[70:71], v[56:57], v[76:77] op_sel:[0,0,1] op_sel_hi:[1,1,0] neg_lo:[0,0,1] neg_hi:[0,0,1]
	v_pk_fma_f32 v[56:57], v[70:71], v[56:57], v[76:77] op_sel:[0,0,1] op_sel_hi:[1,1,0]
	v_and_b32_e32 v59, 0xffff0000, v59
	v_mov_b32_e32 v81, v57
	v_pk_add_f32 v[56:57], v[80:81], v[58:59]
	s_nop 0
	v_cvt_pk_bf16_f32 v58, v56, v57
	ds_write2_b32 v90, v0, v58 offset0:16 offset1:84
	ds_read2_b32 v[58:59], v90 offset0:152 offset1:220
	v_pk_mul_f32 v[80:81], v[72:73], v[56:57]
	s_waitcnt lgkmcnt(0)
; #define LAS __attribute__((address_space(3)))
; __device__ __forceinline__ unsigned cvt_pk_bf16(float lo, float hi) { const bf16v2 v = __builtin_convertvector((f32x2){lo, hi}, bf16v2); return __builtin_bit_cast(unsigned, v); }
; __device__ __forceinline__ float bflo(unsigned w) { return __uint_as_float(w << 16); }
; __device__ __forceinline__ float bfhi(unsigned w) { return __uint_as_float(w & 0xffff0000u); }
; __device__ __forceinline__ u32x2 pack4(const f32x4 a) { u32x2 v; v.x = cvt_pk_bf16(a[0], a[1]); v.y = cvt_pk_bf16(a[2], a[3]); return v; }
; __device__ __forceinline__ float gelu_tanh(float x) { const float e = __builtin_amdgcn_exp2f(x * (-2.302208198f - 0.102943240f * x * x)); return x * __builtin_amdgcn_rcpf(1.0f + e); }
; #define MFMA16(a, b, c) __builtin_amdgcn_mfma_f32_16x16x32_bf16((a), (b), (c), 0, 0, 0)
; __device__ void s5_c_unit(LAS unsigned char* lds, KP& P_, int l, int bc) {
;     ...
; #pragma unroll
;             for (int tl = 0; tl < 16; ++tl) { LAS unsigned* wp = (LAS unsigned*)(XW + tl * 136 + 2 * n); const unsigned w = *wp;
;                 const float nr = lam[0] * xr - lam[1] * xi + bflo(w), ni = lam[0] * xi + lam[1] * xr + bfhi(w); xr = nr; xi = ni; *wp = cvt_pk_bf16(xr, xi); }
;             asm volatile("" ::: "memory");
;             f32x4 acc = (f32x4){0.f, 0.f, 0.f, 0.f};
; #pragma unroll
;             for (int ks = 0; ks < 4; ++ks) { const bf16x8 b = *(const LAS bf16x8*)(XW + fr * 136 + ks * 32 + fq * 8); acc = MFMA16(cf[ks], b, acc); }
;             const int t = blk * 16 + fr; const u32x2 uraw = *(const LAS u32x2*)(UB + t * 264 + g * 16 + fq * 4);
;             const float uv[4] = {bflo(uraw.x), bfhi(uraw.x), bflo(uraw.y), bfhi(uraw.y)}; f32x4 y;
; #pragma unroll
;             for (int j = 0; j < 4; ++j) y[j] = gelu_tanh(acc[j] + dsk[j] * uv[j]);
;             *(LAS u32x2*)(YG + t * 264 + g * 16 + fq * 4) = pack4(y);
;             asm volatile("" ::: "memory");
	v_lshlrev_b32_e32 v76, 16, v58
	v_pk_fma_f32 v[82:83], v[70:71], v[56:57], v[80:81] op_sel:[0,0,1] op_sel_hi:[1,1,0] neg_lo:[0,0,1] neg_hi:[0,0,1]
	v_pk_fma_f32 v[56:57], v[70:71], v[56:57], v[80:81] op_sel:[0,0,1] op_sel_hi:[1,1,0]
	v_and_b32_e32 v77, 0xffff0000, v58
	v_mov_b32_e32 v83, v57
	v_pk_add_f32 v[56:57], v[82:83], v[76:77]
	v_lshlrev_b32_e32 v58, 16, v59
	v_pk_mul_f32 v[76:77], v[72:73], v[56:57]
	v_cvt_pk_bf16_f32 v0, v56, v57
	v_pk_fma_f32 v[80:81], v[70:71], v[56:57], v[76:77] op_sel:[0,0,1] op_sel_hi:[1,1,0] neg_lo:[0,0,1] neg_hi:[0,0,1]
	v_pk_fma_f32 v[56:57], v[70:71], v[56:57], v[76:77] op_sel:[0,0,1] op_sel_hi:[1,1,0]
	v_and_b32_e32 v59, 0xffff0000, v59
	v_mov_b32_e32 v81, v57
	v_pk_add_f32 v[56:57], v[80:81], v[58:59]
	s_nop 0
	v_cvt_pk_bf16_f32 v58, v56, v57
	ds_write2_b32 v90, v0, v58 offset0:152 offset1:220
	ds_read2_b32 v[58:59], v91 offset0:32 offset1:100
	v_pk_mul_f32 v[80:81], v[72:73], v[56:57]
	s_waitcnt lgkmcnt(0)
	v_lshlrev_b32_e32 v76, 16, v58
	v_pk_fma_f32 v[82:83], v[70:71], v[56:57], v[80:81] op_sel:[0,0,1] op_sel_hi:[1,1,0] neg_lo:[0,0,1] neg_hi:[0,0,1]
	v_pk_fma_f32 v[56:57], v[70:71], v[56:57], v[80:81] op_sel:[0,0,1] op_sel_hi:[1,1,0]
	v_and_b32_e32 v77, 0xffff0000, v58
	v_mov_b32_e32 v83, v57
	v_pk_add_f32 v[56:57], v[82:83], v[76:77]
	v_lshlrev_b32_e32 v58, 16, v59
	v_pk_mul_f32 v[76:77], v[72:73], v[56:57]
	v_cvt_pk_bf16_f32 v0, v56, v57
	v_pk_fma_f32 v[80:81], v[70:71], v[56:57], v[76:77] op_sel:[0,0,1] op_sel_hi:[1,1,0] neg_lo:[0,0,1] neg_hi:[0,0,1]
	v_pk_fma_f32 v[56:57], v[70:71], v[56:57], v[76:77] op_sel:[0,0,1] op_sel_hi:[1,1,0]
	v_and_b32_e32 v59, 0xffff0000, v59
	v_mov_b32_e32 v81, v57
	v_pk_add_f32 v[56:57], v[80:81], v[58:59]
	s_nop 0
	v_cvt_pk_bf16_f32 v58, v56, v57
	ds_write2_b32 v91, v0, v58 offset0:32 offset1:100
	ds_read2_b32 v[58:59], v91 offset0:168 offset1:236
	v_pk_mul_f32 v[80:81], v[72:73], v[56:57]
	s_waitcnt lgkmcnt(0)
	v_lshlrev_b32_e32 v76, 16, v58
	v_pk_fma_f32 v[82:83], v[70:71], v[56:57], v[80:81] op_sel:[0,0,1] op_sel_hi:[1,1,0] neg_lo:[0,0,1] neg_hi:[0,0,1]
	v_pk_fma_f32 v[56:57], v[70:71], v[56:57], v[80:81] op_sel:[0,0,1] op_sel_hi:[1,1,0]
	v_and_b32_e32 v77, 0xffff0000, v58
	v_mov_b32_e32 v83, v57
	v_pk_add_f32 v[56:57], v[82:83], v[76:77]
	v_lshlrev_b32_e32 v58, 16, v59
	v_pk_mul_f32 v[76:77], v[72:73], v[56:57]
	v_cvt_pk_bf16_f32 v0, v56, v57
	v_pk_fma_f32 v[80:81], v[70:71], v[56:57], v[76:77] op_sel:[0,0,1] op_sel_hi:[1,1,0] neg_lo:[0,0,1] neg_hi:[0,0,1]
	v_pk_fma_f32 v[56:57], v[70:71], v[56:57], v[76:77] op_sel:[0,0,1] op_sel_hi:[1,1,0]
	v_and_b32_e32 v59, 0xffff0000, v59
	v_mov_b32_e32 v81, v57
	v_pk_add_f32 v[56:57], v[80:81], v[58:59]
	s_nop 0
	v_cvt_pk_bf16_f32 v58, v56, v57
	ds_write2_b32 v91, v0, v58 offset0:168 offset1:236
	ds_read2_b32 v[58:59], v92 offset0:48 offset1:116
	v_pk_mul_f32 v[80:81], v[72:73], v[56:57]
	s_waitcnt lgkmcnt(0)
	v_lshlrev_b32_e32 v76, 16, v58
	v_pk_fma_f32 v[82:83], v[70:71], v[56:57], v[80:81] op_sel:[0,0,1] op_sel_hi:[1,1,0] neg_lo:[0,0,1] neg_hi:[0,0,1]
	v_pk_fma_f32 v[56:57], v[70:71], v[56:57], v[80:81] op_sel:[0,0,1] op_sel_hi:[1,1,0]
	v_and_b32_e32 v77, 0xffff0000, v58
	v_mov_b32_e32 v83, v57
	v_pk_add_f32 v[56:57], v[82:83], v[76:77]
	v_lshlrev_b32_e32 v58, 16, v59
	v_pk_mul_f32 v[76:77], v[72:73], v[56:57]
	v_cvt_pk_bf16_f32 v0, v56, v57
	v_pk_fma_f32 v[80:81], v[70:71], v[56:57], v[76:77] op_sel:[0,0,1] op_sel_hi:[1,1,0] neg_lo:[0,0,1] neg_hi:[0,0,1]
	v_pk_fma_f32 v[56:57], v[70:71], v[56:57], v[76:77] op_sel:[0,0,1] op_sel_hi:[1,1,0]
	v_and_b32_e32 v59, 0xffff0000, v59
	v_mov_b32_e32 v81, v57
	v_pk_add_f32 v[56:57], v[80:81], v[58:59]
	s_nop 0
	v_cvt_pk_bf16_f32 v58, v56, v57
	ds_write2_b32 v92, v0, v58 offset0:48 offset1:116
	ds_read2_b32 v[58:59], v92 offset0:184 offset1:252
	v_pk_mul_f32 v[80:81], v[72:73], v[56:57]
	s_waitcnt lgkmcnt(0)
	v_lshlrev_b32_e32 v76, 16, v58
	v_pk_fma_f32 v[82:83], v[70:71], v[56:57], v[80:81] op_sel:[0,0,1] op_sel_hi:[1,1,0] neg_lo:[0,0,1] neg_hi:[0,0,1]
	v_pk_fma_f32 v[56:57], v[70:71], v[56:57], v[80:81] op_sel:[0,0,1] op_sel_hi:[1,1,0]
	v_and_b32_e32 v77, 0xffff0000, v58
	v_mov_b32_e32 v83, v57
	v_pk_add_f32 v[56:57], v[82:83], v[76:77]
	v_lshlrev_b32_e32 v58, 16, v59
	v_pk_mul_f32 v[76:77], v[72:73], v[56:57]
	v_cvt_pk_bf16_f32 v0, v56, v57
	v_pk_fma_f32 v[80:81], v[70:71], v[56:57], v[76:77] op_sel:[0,0,1] op_sel_hi:[1,1,0] neg_lo:[0,0,1] neg_hi:[0,0,1]
	v_pk_fma_f32 v[56:57], v[70:71], v[56:57], v[76:77] op_sel:[0,0,1] op_sel_hi:[1,1,0]
	v_and_b32_e32 v59, 0xffff0000, v59
	v_mov_b32_e32 v81, v57
	v_pk_add_f32 v[76:77], v[80:81], v[58:59]
	s_nop 0
	v_cvt_pk_bf16_f32 v56, v76, v77
	ds_write2_b32 v92, v0, v56 offset0:184 offset1:252
	ds_read_b128 v[56:59], v93 offset:33792
	ds_read_b128 v[80:83], v93 offset:33856
	v_add_u32_e32 v0, s23, v61
	ds_read_b64 v[84:85], v0 offset:256
	s_waitcnt vmcnt(3) lgkmcnt(2)
	v_mfma_f32_16x16x32_bf16 v[56:59], v[40:43], v[56:59], 0
	v_add_u32_e32 v0, 0x10d00, v0
	s_addk_i32 s23, 0x2100
	s_waitcnt lgkmcnt(0)
	v_lshlrev_b32_e32 v86, 16, v84
	s_waitcnt vmcnt(2)
	v_mfma_f32_16x16x32_bf16 v[56:59], v[44:47], v[80:83], v[56:59]
	ds_read_b128 v[80:83], v93 offset:33920
	v_and_b32_e32 v87, 0xffff0000, v84
	s_cmpk_eq_u32 s23, 0x8400
	s_waitcnt vmcnt(1) lgkmcnt(0)
	v_mfma_f32_16x16x32_bf16 v[56:59], v[48:51], v[80:83], v[56:59]
	ds_read_b128 v[80:83], v93 offset:33984
	s_waitcnt vmcnt(0) lgkmcnt(0)
	v_mfma_f32_16x16x32_bf16 v[56:59], v[52:55], v[80:83], v[56:59]
	s_nop 7
	v_pk_fma_f32 v[56:57], v[246:247], v[86:87], v[56:57]
	s_nop 0
	v_mul_f32_e32 v79, 0x3dd2d3e8, v56
	v_fma_f32 v79, -v56, v79, s92
	v_mul_f32_e32 v79, v56, v79
	v_exp_f32_e32 v79, v79
	s_nop 0
	v_add_f32_e32 v79, 1.0, v79
	v_rcp_f32_e32 v80, v79
	v_mul_f32_e32 v79, 0x3dd2d3e8, v57
	v_fma_f32 v79, -v57, v79, s92
	v_mul_f32_e32 v79, v57, v79
	v_exp_f32_e32 v79, v79
	s_nop 0
	v_add_f32_e32 v79, 1.0, v79
	v_rcp_f32_e32 v81, v79
	s_nop 0
	v_pk_mul_f32 v[56:57], v[56:57], v[80:81]
	v_lshlrev_b32_e32 v80, 16, v85
	v_and_b32_e32 v81, 0xffff0000, v85
	v_pk_fma_f32 v[58:59], v[248:249], v[80:81], v[58:59]
	v_cvt_pk_bf16_f32 v56, v56, v57
	v_mul_f32_e32 v79, 0x3dd2d3e8, v58
	v_fma_f32 v79, -v58, v79, s92
	v_mul_f32_e32 v79, v58, v79
	v_exp_f32_e32 v79, v79
	s_nop 0
	v_add_f32_e32 v79, 1.0, v79
	v_rcp_f32_e32 v80, v79
	v_mul_f32_e32 v79, 0x3dd2d3e8, v59
	v_fma_f32 v79, -v59, v79, s92
	v_mul_f32_e32 v79, v59, v79
	v_exp_f32_e32 v79, v79
	s_nop 0
	v_add_f32_e32 v79, 1.0, v79
	v_rcp_f32_e32 v81, v79
	s_nop 0
	v_pk_mul_f32 v[58:59], v[58:59], v[80:81]
	s_nop 0
	v_cvt_pk_bf16_f32 v57, v58, v59
	ds_write_b64 v0, v[56:57]
	v_mov_b32_e32 v0, v77
	s_cbranch_scc1 .LBB0_339
